# v22 + in-proj and FFN gate/up GEMMs: accumulator zeroing moved into the first K-trip's LDS-read shadow (skipped on later trips) instead of before the K-loop
# baseline (speedup 1.0000x reference)
; #define PG8_STAGE(bufoff, gbase, voff) do { _Pragma("unroll") for (int _i = 0; _i < 2; ++_i) \
;         __builtin_amdgcn_global_load_lds((const unsigned*)((const char*)(gbase) + (voff)[_i]), (LAS unsigned*)(lds + (bufoff) + ldsw + _i * 8192), 16, 0, 0); } while (0)
; #define PG8_LDA(dst, b, h) do { _Pragma("unroll") for (int m = 0; m < 4; ++m) _Pragma("unroll") for (int k = 0; k < 2; ++k) dst[m][k] = *(const LAS bf16x8*)(lds + PG8_SA(b, h) + aoff + m * 2048 + k * 1024); } while (0)
; #define PG8_LDB(dst, b, h) do { _Pragma("unroll") for (int n = 0; n < 2; ++n) _Pragma("unroll") for (int k = 0; k < 2; ++k) dst[n][k] = *(const LAS bf16x8*)(lds + PG8_SB(b, h) + boff + n * 2048 + k * 1024); } while (0)
; #define PG8_MMA(ai, bj, At, Bt) do { __builtin_amdgcn_s_setprio(1); _Pragma("unroll") for (int m = 0; m < 4; ++m) _Pragma("unroll") for (int n = 0; n < 2; ++n) _Pragma("unroll") for (int k = 0; k < 2; ++k) \
;         acc[ai][bj][m][n] = __builtin_amdgcn_mfma_f32_16x16x32_bf16(Bt[n][k], At[m][k], acc[ai][bj][m][n], 0, 0, 0); __builtin_amdgcn_s_setprio(0); } while (0)
; #define PG8_WAIT_V(n) asm volatile("s_waitcnt vmcnt(" #n ")" ::: "memory")
; #define PG8_WAIT_L(n) asm volatile("s_waitcnt lgkmcnt(" #n ")" ::: "memory")
; #define PG8_BAR __builtin_amdgcn_s_barrier()
; #define PG8_SCHED __builtin_amdgcn_sched_barrier(0)
; template <class Epi, bool ALIGN_EPI>
; __device__ __forceinline__ void gemm_phase(LAS unsigned char* lds, const Gemm g, const StaticOrder& S, const Epi& E) {
;     ...
;         const bool has_next = S.next(ui + 1, nxt);
;         const char* nA = has_next ? (const char*)g.A + (size_t)nxt.pm * tstepA : cA; const char* nB = has_next ? (const char*)g.Bt + (size_t)nxt.pn * tstepB : cB;
;         for (int t = 0; t < nt; t += 2) {
;             const bool last = (t == nt - 2);
;             const char* a1 = cA + (size_t)(t + 1) * kstep;
;             const char* a2 = last ? nA : cA + (size_t)(t + 2) * kstep; const char* b2 = last ? nB : cB + (size_t)(t + 2) * kstep;
;             const char* a3 = a2 + kstep; const char* b3 = b2 + kstep;
;             PG8_LDB(B0, 0, 0); PG8_LDB(B1, 0, 1); PG8_SCHED; PG8_LDA(At, 0, 0); PG8_STAGE(PG8_SA(1, 1), a1 + hstepA, voffA);
;             PG8_WAIT_V(8); PG8_WAIT_L(0); PG8_BAR; PG8_MMA(0, 0, At, B0); PG8_MMA(0, 1, At, B1); PG8_BAR; PG8_SCHED;
.LBB0_1261:
	s_ashr_i32 s57, s56, 31
	s_lshl_b64 s[16:17], s[56:57], 19
	s_add_u32 s16, s8, s16
	s_addc_u32 s17, s9, s17
	s_and_b64 s[18:19], s[40:41], exec
	s_cselect_b32 s24, s17, s21
	s_cselect_b32 s25, s16, s20
	s_ashr_i32 s61, s60, 31
	s_lshl_b64 s[18:19], s[60:61], 19
	s_add_u32 s18, s80, s18
	v_readlane_b32 s28, v251, 51
	s_addc_u32 s19, s28, s19
	s_and_b64 s[28:29], s[40:41], exec
	s_cselect_b32 s28, s19, s23
	s_cselect_b32 s29, s18, s22
	s_add_u32 s46, s22, 0x100
	s_addc_u32 s47, s23, 0
	s_add_u32 s20, s20, 0x40080
	s_addc_u32 s21, s21, 0
	s_mov_b32 s54, -2
	s_waitcnt vmcnt(0)
.LBB0_1262:
	s_add_u32 s22, s20, 0xfffc0080
	s_addc_u32 s23, s21, -1
	s_add_i32 s30, 0, 0x10000
	s_cmp_eq_u32 s54, 12
	s_cselect_b32 s51, s24, s23
	s_cselect_b32 s50, s25, s22
	s_cselect_b32 s23, s28, s47
	s_cselect_b32 s22, s29, s46
	s_add_i32 s31, 0, 0x14000
	v_add_u32_e32 v154, s30, v167
	v_add_u32_e32 v162, s31, v167
	ds_read_b128 v[130:133], v154
	ds_read_b128 v[134:137], v154 offset:1024
	ds_read_b128 v[138:141], v154 offset:2048
	ds_read_b128 v[154:157], v154 offset:3072
	ds_read_b128 v[158:161], v162
	ds_read_b128 v[176:179], v162 offset:1024
	ds_read_b128 v[204:207], v162 offset:2048
	ds_read_b128 v[208:211], v162 offset:3072
	v_lshl_add_u64 v[162:163], s[20:21], 0, v[152:153]
	s_add_i32 m0, s96, 0xc000
	ds_read_b128 v[212:215], v175
	ds_read_b128 v[216:219], v175 offset:1024
	ds_read_b128 v[220:223], v175 offset:2048
	ds_read_b128 v[224:227], v175 offset:3072
	ds_read_b128 v[228:231], v175 offset:4096
	ds_read_b128 v[232:235], v175 offset:5120
	ds_read_b128 v[236:239], v175 offset:6144
	ds_read_b128 v[240:243], v175 offset:7168
	global_load_lds_dwordx4 v[162:163], off
	v_lshl_add_u64 v[162:163], s[20:21], 0, v[150:151]
	s_add_i32 m0, s96, 0xe000
	s_nop 0
	global_load_lds_dwordx4 v[162:163], off
	s_cmp_lg_u32 s54, -2
	s_cbranch_scc1 .Lmy_nz_b
	v_mov_b64_e32 v[0:1], 0
	v_mov_b64_e32 v[2:3], 0
	v_mov_b64_e32 v[6:7], 0
	v_mov_b64_e32 v[8:9], 0
	v_mov_b64_e32 v[10:11], 0
	v_mov_b64_e32 v[12:13], 0
	v_mov_b64_e32 v[14:15], 0
	v_mov_b64_e32 v[16:17], 0
	v_mov_b64_e32 v[18:19], 0
	v_mov_b64_e32 v[20:21], 0
	v_mov_b64_e32 v[22:23], 0
	v_mov_b64_e32 v[24:25], 0
	v_mov_b64_e32 v[26:27], 0
	v_mov_b64_e32 v[28:29], 0
	v_mov_b64_e32 v[30:31], 0
	v_mov_b64_e32 v[32:33], 0
	v_mov_b64_e32 v[34:35], 0
	v_mov_b64_e32 v[36:37], 0
	v_mov_b64_e32 v[38:39], 0
	v_mov_b64_e32 v[40:41], 0
	v_mov_b64_e32 v[42:43], 0
	v_mov_b64_e32 v[44:45], 0
	v_mov_b64_e32 v[46:47], 0
	v_mov_b64_e32 v[48:49], 0
	v_mov_b64_e32 v[50:51], 0
	v_mov_b64_e32 v[52:53], 0
	v_mov_b64_e32 v[54:55], 0
	v_mov_b64_e32 v[56:57], 0
	v_mov_b64_e32 v[58:59], 0
	v_mov_b64_e32 v[60:61], 0
	v_mov_b64_e32 v[62:63], 0
	v_mov_b64_e32 v[64:65], 0
	v_mov_b64_e32 v[66:67], 0
	v_mov_b64_e32 v[68:69], 0
	v_mov_b64_e32 v[70:71], 0
	v_mov_b64_e32 v[72:73], 0
	v_mov_b64_e32 v[74:75], 0
	v_mov_b64_e32 v[76:77], 0
	v_mov_b64_e32 v[78:79], 0
	v_mov_b64_e32 v[80:81], 0
	v_mov_b64_e32 v[82:83], 0
	v_mov_b64_e32 v[84:85], 0
	v_mov_b64_e32 v[86:87], 0
	v_mov_b64_e32 v[88:89], 0
	v_mov_b64_e32 v[90:91], 0
	v_mov_b64_e32 v[92:93], 0
	v_mov_b64_e32 v[94:95], 0
	v_mov_b64_e32 v[96:97], 0
	v_mov_b64_e32 v[98:99], 0
	v_mov_b64_e32 v[100:101], 0
	v_mov_b64_e32 v[102:103], 0
	v_mov_b64_e32 v[104:105], 0
	v_mov_b64_e32 v[106:107], 0
	v_mov_b64_e32 v[108:109], 0
	v_mov_b64_e32 v[110:111], 0
	v_mov_b64_e32 v[112:113], 0
	v_mov_b64_e32 v[114:115], 0
	v_mov_b64_e32 v[116:117], 0
	v_mov_b64_e32 v[118:119], 0
	v_mov_b64_e32 v[120:121], 0
	v_mov_b64_e32 v[122:123], 0
	v_mov_b64_e32 v[124:125], 0
	v_mov_b64_e32 v[126:127], 0
	v_mov_b64_e32 v[128:129], 0
.Lmy_nz_b:
	s_waitcnt vmcnt(8)
	s_waitcnt lgkmcnt(0)
	s_barrier
	s_setprio 1
	s_waitcnt lgkmcnt(0)
	v_mfma_f32_16x16x32_bf16 v[126:129], v[130:133], v[212:215], v[126:129]
	v_mfma_f32_16x16x32_bf16 v[118:121], v[138:141], v[212:215], v[118:121]
	v_mfma_f32_16x16x32_bf16 v[110:113], v[130:133], v[220:223], v[110:113]
	v_mfma_f32_16x16x32_bf16 v[102:105], v[138:141], v[220:223], v[102:105]
	v_mfma_f32_16x16x32_bf16 v[94:97], v[130:133], v[228:231], v[94:97]
	v_mfma_f32_16x16x32_bf16 v[86:89], v[138:141], v[228:231], v[86:89]
	v_mfma_f32_16x16x32_bf16 v[78:81], v[130:133], v[236:239], v[78:81]
	v_mfma_f32_16x16x32_bf16 v[70:73], v[138:141], v[236:239], v[70:73]
	v_mfma_f32_16x16x32_bf16 v[126:129], v[134:137], v[216:219], v[126:129]
	v_mfma_f32_16x16x32_bf16 v[118:121], v[154:157], v[216:219], v[118:121]
	v_mfma_f32_16x16x32_bf16 v[110:113], v[134:137], v[224:227], v[110:113]
	v_mfma_f32_16x16x32_bf16 v[102:105], v[154:157], v[224:227], v[102:105]
	v_mfma_f32_16x16x32_bf16 v[94:97], v[134:137], v[232:235], v[94:97]
	v_mfma_f32_16x16x32_bf16 v[86:89], v[154:157], v[232:235], v[86:89]
	v_mfma_f32_16x16x32_bf16 v[78:81], v[134:137], v[240:243], v[78:81]
	v_mfma_f32_16x16x32_bf16 v[70:73], v[154:157], v[240:243], v[70:73]
	s_setprio 0
	s_setprio 1
	v_mfma_f32_16x16x32_bf16 v[122:125], v[158:161], v[212:215], v[122:125]
	v_mfma_f32_16x16x32_bf16 v[114:117], v[204:207], v[212:215], v[114:117]
	v_mfma_f32_16x16x32_bf16 v[106:109], v[158:161], v[220:223], v[106:109]
	v_mfma_f32_16x16x32_bf16 v[98:101], v[204:207], v[220:223], v[98:101]
	v_mfma_f32_16x16x32_bf16 v[90:93], v[158:161], v[228:231], v[90:93]
	v_mfma_f32_16x16x32_bf16 v[82:85], v[204:207], v[228:231], v[82:85]
	v_mfma_f32_16x16x32_bf16 v[74:77], v[158:161], v[236:239], v[74:77]
	v_mfma_f32_16x16x32_bf16 v[66:69], v[204:207], v[236:239], v[66:69]
	v_mfma_f32_16x16x32_bf16 v[122:125], v[176:179], v[216:219], v[122:125]
	v_mfma_f32_16x16x32_bf16 v[114:117], v[208:211], v[216:219], v[114:117]
	v_mfma_f32_16x16x32_bf16 v[106:109], v[176:179], v[224:227], v[106:109]
	v_mfma_f32_16x16x32_bf16 v[98:101], v[208:211], v[224:227], v[98:101]
	v_mfma_f32_16x16x32_bf16 v[90:93], v[176:179], v[232:235], v[90:93]
	v_mfma_f32_16x16x32_bf16 v[82:85], v[208:211], v[232:235], v[82:85]
	v_mfma_f32_16x16x32_bf16 v[74:77], v[176:179], v[240:243], v[74:77]
	v_mfma_f32_16x16x32_bf16 v[66:69], v[208:211], v[240:243], v[66:69]
	s_setprio 0
	s_barrier
; #define PG8_STAGE(bufoff, gbase, voff) do { _Pragma("unroll") for (int _i = 0; _i < 2; ++_i) \
;         __builtin_amdgcn_global_load_lds((const unsigned*)((const char*)(gbase) + (voff)[_i]), (LAS unsigned*)(lds + (bufoff) + ldsw + _i * 8192), 16, 0, 0); } while (0)
; #define PG8_LDA(dst, b, h) do { _Pragma("unroll") for (int m = 0; m < 4; ++m) _Pragma("unroll") for (int k = 0; k < 2; ++k) dst[m][k] = *(const LAS bf16x8*)(lds + PG8_SA(b, h) + aoff + m * 2048 + k * 1024); } while (0)
; #define PG8_LDB(dst, b, h) do { _Pragma("unroll") for (int n = 0; n < 2; ++n) _Pragma("unroll") for (int k = 0; k < 2; ++k) dst[n][k] = *(const LAS bf16x8*)(lds + PG8_SB(b, h) + boff + n * 2048 + k * 1024); } while (0)
; #define PG8_MMA(ai, bj, At, Bt) do { __builtin_amdgcn_s_setprio(1); _Pragma("unroll") for (int m = 0; m < 4; ++m) _Pragma("unroll") for (int n = 0; n < 2; ++n) _Pragma("unroll") for (int k = 0; k < 2; ++k) \
;         acc[ai][bj][m][n] = __builtin_amdgcn_mfma_f32_16x16x32_bf16(Bt[n][k], At[m][k], acc[ai][bj][m][n], 0, 0, 0); __builtin_amdgcn_s_setprio(0); } while (0)
; #define PG8_WAIT_V(n) asm volatile("s_waitcnt vmcnt(" #n ")" ::: "memory")
; #define PG8_WAIT_L(n) asm volatile("s_waitcnt lgkmcnt(" #n ")" ::: "memory")
; #define PG8_BAR __builtin_amdgcn_s_barrier()
; #define PG8_SCHED __builtin_amdgcn_sched_barrier(0)
; template <class Epi, bool ALIGN_EPI>
; __device__ __forceinline__ void gemm_phase(LAS unsigned char* lds, const Gemm g, const StaticOrder& S, const Epi& E) {
;     ...
;             PG8_LDA(At, 0, 1); PG8_STAGE(PG8_SB(0, 0), b2, voffB); PG8_STAGE(PG8_SB(0, 1), b2 + hstepB, voffB); PG8_STAGE(PG8_SA(0, 0), a2, voffA);
;             PG8_WAIT_V(8); PG8_WAIT_L(0); PG8_BAR; PG8_MMA(1, 0, At, B0); PG8_MMA(1, 1, At, B1); PG8_BAR; PG8_SCHED;
;             PG8_LDB(B0, 1, 0); PG8_LDB(B1, 1, 1); PG8_SCHED; PG8_LDA(At, 1, 0); PG8_STAGE(PG8_SA(0, 1), a2 + hstepA, voffA);
;             PG8_WAIT_V(8); PG8_WAIT_L(0); PG8_BAR; PG8_MMA(0, 0, At, B0); PG8_MMA(0, 1, At, B1); PG8_BAR; PG8_SCHED;
	s_add_i32 s30, s30, s84
	v_lshl_add_u64 v[162:163], s[22:23], 0, v[4:5]
	s_mov_b32 m0, s30
	ds_read_b128 v[212:215], v175 offset:16384
	ds_read_b128 v[216:219], v175 offset:17408
	ds_read_b128 v[220:223], v175 offset:18432
	ds_read_b128 v[224:227], v175 offset:19456
	ds_read_b128 v[228:231], v175 offset:20480
	ds_read_b128 v[232:235], v175 offset:21504
	ds_read_b128 v[236:239], v175 offset:22528
	ds_read_b128 v[240:243], v175 offset:23552
	global_load_lds_dwordx4 v[162:163], off
	s_add_i32 m0, s30, 0x2000
	s_add_u32 s58, s22, 0x40000
	v_lshl_add_u64 v[168:169], s[22:23], 0, v[142:143]
	s_addc_u32 s59, s23, 0
	s_add_i32 s30, s31, s84
	global_load_lds_dwordx4 v[168:169], off
	v_lshl_add_u64 v[172:173], s[58:59], 0, v[4:5]
	s_mov_b32 m0, s30
	v_lshl_add_u64 v[180:181], s[50:51], 0, v[144:145]
	global_load_lds_dwordx4 v[172:173], off
	v_lshl_add_u64 v[172:173], s[58:59], 0, v[142:143]
	s_add_i32 m0, s30, 0x2000
	s_nop 0
	global_load_lds_dwordx4 v[172:173], off
	v_lshl_add_u64 v[172:173], s[50:51], 0, v[146:147]
	s_mov_b32 m0, s96
	s_nop 0
	global_load_lds_dwordx4 v[172:173], off
	s_mov_b32 m0, s97
	s_nop 0
	global_load_lds_dwordx4 v[180:181], off
	s_waitcnt vmcnt(8)
	s_waitcnt lgkmcnt(0)
	s_barrier
	s_setprio 1
	s_waitcnt lgkmcnt(0)
	v_mfma_f32_16x16x32_bf16 v[62:65], v[130:133], v[212:215], v[62:65]
	v_mfma_f32_16x16x32_bf16 v[54:57], v[138:141], v[212:215], v[54:57]
	v_mfma_f32_16x16x32_bf16 v[46:49], v[130:133], v[220:223], v[46:49]
	v_mfma_f32_16x16x32_bf16 v[38:41], v[138:141], v[220:223], v[38:41]
	v_mfma_f32_16x16x32_bf16 v[30:33], v[130:133], v[228:231], v[30:33]
	v_mfma_f32_16x16x32_bf16 v[22:25], v[138:141], v[228:231], v[22:25]
	v_mfma_f32_16x16x32_bf16 v[14:17], v[130:133], v[236:239], v[14:17]
	v_mfma_f32_16x16x32_bf16 v[6:9], v[138:141], v[236:239], v[6:9]
	v_mfma_f32_16x16x32_bf16 v[62:65], v[134:137], v[216:219], v[62:65]
	v_mfma_f32_16x16x32_bf16 v[54:57], v[154:157], v[216:219], v[54:57]
	v_mfma_f32_16x16x32_bf16 v[46:49], v[134:137], v[224:227], v[46:49]
	v_mfma_f32_16x16x32_bf16 v[38:41], v[154:157], v[224:227], v[38:41]
	v_mfma_f32_16x16x32_bf16 v[30:33], v[134:137], v[232:235], v[30:33]
	v_mfma_f32_16x16x32_bf16 v[22:25], v[154:157], v[232:235], v[22:25]
	v_mfma_f32_16x16x32_bf16 v[14:17], v[134:137], v[240:243], v[14:17]
	v_mfma_f32_16x16x32_bf16 v[6:9], v[154:157], v[240:243], v[6:9]
	s_setprio 0
	s_setprio 1
	v_mfma_f32_16x16x32_bf16 v[58:61], v[158:161], v[212:215], v[58:61]
	v_mfma_f32_16x16x32_bf16 v[50:53], v[204:207], v[212:215], v[50:53]
	v_mfma_f32_16x16x32_bf16 v[42:45], v[158:161], v[220:223], v[42:45]
	v_mfma_f32_16x16x32_bf16 v[34:37], v[204:207], v[220:223], v[34:37]
	v_mfma_f32_16x16x32_bf16 v[26:29], v[158:161], v[228:231], v[26:29]
	v_mfma_f32_16x16x32_bf16 v[18:21], v[204:207], v[228:231], v[18:21]
	v_mfma_f32_16x16x32_bf16 v[10:13], v[158:161], v[236:239], v[10:13]
	v_mfma_f32_16x16x32_bf16 v[0:3], v[204:207], v[236:239], v[0:3]
	v_mfma_f32_16x16x32_bf16 v[58:61], v[176:179], v[216:219], v[58:61]
	v_mfma_f32_16x16x32_bf16 v[50:53], v[208:211], v[216:219], v[50:53]
	v_mfma_f32_16x16x32_bf16 v[42:45], v[176:179], v[224:227], v[42:45]
	v_mfma_f32_16x16x32_bf16 v[34:37], v[208:211], v[224:227], v[34:37]
	v_mfma_f32_16x16x32_bf16 v[26:29], v[176:179], v[232:235], v[26:29]
	v_mfma_f32_16x16x32_bf16 v[18:21], v[208:211], v[232:235], v[18:21]
	v_mfma_f32_16x16x32_bf16 v[10:13], v[176:179], v[240:243], v[10:13]
	v_mfma_f32_16x16x32_bf16 v[0:3], v[208:211], v[240:243], v[0:3]
	s_setprio 0
	s_barrier
	s_add_i32 s30, 0, 0x18000
	s_add_i32 s31, 0, 0x1c000
	v_add_u32_e32 v154, s30, v167
	v_add_u32_e32 v164, s31, v167
	ds_read_b128 v[130:133], v154
	ds_read_b128 v[134:137], v154 offset:1024
	ds_read_b128 v[138:141], v154 offset:2048
	ds_read_b128 v[154:157], v154 offset:3072
	ds_read_b128 v[158:161], v164
	ds_read_b128 v[176:179], v164 offset:1024
	ds_read_b128 v[204:207], v164 offset:2048
	ds_read_b128 v[208:211], v164 offset:3072
	s_add_u32 s50, s50, 0x40000
	s_addc_u32 s51, s51, 0
	s_mov_b32 m0, s14
	v_lshl_add_u64 v[244:245], s[50:51], 0, v[146:147]
	ds_read_b128 v[212:215], v175 offset:32768
	ds_read_b128 v[216:219], v175 offset:33792
	ds_read_b128 v[220:223], v175 offset:34816
	ds_read_b128 v[224:227], v175 offset:35840
	ds_read_b128 v[228:231], v175 offset:36864
	ds_read_b128 v[232:235], v175 offset:37888
	ds_read_b128 v[236:239], v175 offset:38912
	ds_read_b128 v[240:243], v175 offset:39936
	global_load_lds_dwordx4 v[244:245], off
	v_lshl_add_u64 v[244:245], s[50:51], 0, v[144:145]
	s_mov_b32 m0, s15
	s_nop 0
	global_load_lds_dwordx4 v[244:245], off
	s_waitcnt vmcnt(8)
	s_waitcnt lgkmcnt(0)
	s_barrier
; #define PG8_STAGE(bufoff, gbase, voff) do { _Pragma("unroll") for (int _i = 0; _i < 2; ++_i) \
;         __builtin_amdgcn_global_load_lds((const unsigned*)((const char*)(gbase) + (voff)[_i]), (LAS unsigned*)(lds + (bufoff) + ldsw + _i * 8192), 16, 0, 0); } while (0)
; #define PG8_LDA(dst, b, h) do { _Pragma("unroll") for (int m = 0; m < 4; ++m) _Pragma("unroll") for (int k = 0; k < 2; ++k) dst[m][k] = *(const LAS bf16x8*)(lds + PG8_SA(b, h) + aoff + m * 2048 + k * 1024); } while (0)
; #define PG8_MMA(ai, bj, At, Bt) do { __builtin_amdgcn_s_setprio(1); _Pragma("unroll") for (int m = 0; m < 4; ++m) _Pragma("unroll") for (int n = 0; n < 2; ++n) _Pragma("unroll") for (int k = 0; k < 2; ++k) \
;         acc[ai][bj][m][n] = __builtin_amdgcn_mfma_f32_16x16x32_bf16(Bt[n][k], At[m][k], acc[ai][bj][m][n], 0, 0, 0); __builtin_amdgcn_s_setprio(0); } while (0)
; #define PG8_WAIT_V(n) asm volatile("s_waitcnt vmcnt(" #n ")" ::: "memory")
; #define PG8_WAIT_L(n) asm volatile("s_waitcnt lgkmcnt(" #n ")" ::: "memory")
; #define PG8_BAR __builtin_amdgcn_s_barrier()
; #define PG8_SCHED __builtin_amdgcn_sched_barrier(0)
; template <class Epi, bool ALIGN_EPI>
; __device__ __forceinline__ void gemm_phase(LAS unsigned char* lds, const Gemm g, const StaticOrder& S, const Epi& E) {
;     ...
;             PG8_WAIT_V(8); PG8_WAIT_L(0); PG8_BAR; PG8_MMA(0, 0, At, B0); PG8_MMA(0, 1, At, B1); PG8_BAR; PG8_SCHED;
;             PG8_LDA(At, 1, 1); PG8_STAGE(PG8_SB(1, 0), b3, voffB); PG8_STAGE(PG8_SB(1, 1), b3 + hstepB, voffB); PG8_STAGE(PG8_SA(1, 0), a3, voffA);
;             PG8_WAIT_V(8); PG8_WAIT_L(0); PG8_BAR; PG8_MMA(1, 0, At, B0); PG8_MMA(1, 1, At, B1); PG8_BAR; PG8_SCHED;
;         }
;         if constexpr (ALIGN_EPI) { if (wr == 0) PG8_BAR; }
	s_setprio 1
	s_waitcnt lgkmcnt(0)
	v_mfma_f32_16x16x32_bf16 v[126:129], v[130:133], v[212:215], v[126:129]
	v_mfma_f32_16x16x32_bf16 v[118:121], v[138:141], v[212:215], v[118:121]
	v_mfma_f32_16x16x32_bf16 v[110:113], v[130:133], v[220:223], v[110:113]
	v_mfma_f32_16x16x32_bf16 v[102:105], v[138:141], v[220:223], v[102:105]
	v_mfma_f32_16x16x32_bf16 v[94:97], v[130:133], v[228:231], v[94:97]
	v_mfma_f32_16x16x32_bf16 v[86:89], v[138:141], v[228:231], v[86:89]
	v_mfma_f32_16x16x32_bf16 v[78:81], v[130:133], v[236:239], v[78:81]
	v_mfma_f32_16x16x32_bf16 v[70:73], v[138:141], v[236:239], v[70:73]
	v_mfma_f32_16x16x32_bf16 v[126:129], v[134:137], v[216:219], v[126:129]
	v_mfma_f32_16x16x32_bf16 v[118:121], v[154:157], v[216:219], v[118:121]
	v_mfma_f32_16x16x32_bf16 v[110:113], v[134:137], v[224:227], v[110:113]
	v_mfma_f32_16x16x32_bf16 v[102:105], v[154:157], v[224:227], v[102:105]
	v_mfma_f32_16x16x32_bf16 v[94:97], v[134:137], v[232:235], v[94:97]
	v_mfma_f32_16x16x32_bf16 v[86:89], v[154:157], v[232:235], v[86:89]
	v_mfma_f32_16x16x32_bf16 v[78:81], v[134:137], v[240:243], v[78:81]
	v_mfma_f32_16x16x32_bf16 v[70:73], v[154:157], v[240:243], v[70:73]
	s_setprio 0
	s_setprio 1
	v_mfma_f32_16x16x32_bf16 v[122:125], v[158:161], v[212:215], v[122:125]
	v_mfma_f32_16x16x32_bf16 v[114:117], v[204:207], v[212:215], v[114:117]
	v_mfma_f32_16x16x32_bf16 v[106:109], v[158:161], v[220:223], v[106:109]
	v_mfma_f32_16x16x32_bf16 v[98:101], v[204:207], v[220:223], v[98:101]
	v_mfma_f32_16x16x32_bf16 v[90:93], v[158:161], v[228:231], v[90:93]
	v_mfma_f32_16x16x32_bf16 v[82:85], v[204:207], v[228:231], v[82:85]
	v_mfma_f32_16x16x32_bf16 v[74:77], v[158:161], v[236:239], v[74:77]
	v_mfma_f32_16x16x32_bf16 v[66:69], v[204:207], v[236:239], v[66:69]
	v_mfma_f32_16x16x32_bf16 v[122:125], v[176:179], v[216:219], v[122:125]
	v_mfma_f32_16x16x32_bf16 v[114:117], v[208:211], v[216:219], v[114:117]
	v_mfma_f32_16x16x32_bf16 v[106:109], v[176:179], v[224:227], v[106:109]
	v_mfma_f32_16x16x32_bf16 v[98:101], v[208:211], v[224:227], v[98:101]
	v_mfma_f32_16x16x32_bf16 v[90:93], v[176:179], v[232:235], v[90:93]
	v_mfma_f32_16x16x32_bf16 v[82:85], v[208:211], v[232:235], v[82:85]
	v_mfma_f32_16x16x32_bf16 v[74:77], v[176:179], v[240:243], v[74:77]
	v_mfma_f32_16x16x32_bf16 v[66:69], v[208:211], v[240:243], v[66:69]
	s_setprio 0
	s_barrier
	s_add_i32 s30, s30, s84
	v_lshl_add_u64 v[162:163], v[162:163], 0, s[90:91]
	s_mov_b32 m0, s30
	ds_read_b128 v[212:215], v175 offset:49152
	ds_read_b128 v[216:219], v175 offset:50176
	ds_read_b128 v[220:223], v175 offset:51200
	ds_read_b128 v[224:227], v175 offset:52224
	ds_read_b128 v[228:231], v175 offset:53248
	ds_read_b128 v[232:235], v175 offset:54272
	ds_read_b128 v[236:239], v175 offset:55296
	ds_read_b128 v[240:243], v175 offset:56320
	global_load_lds_dwordx4 v[162:163], off
	s_add_i32 m0, s30, 0x2000
	s_add_u32 s22, s22, 0x40080
	v_lshl_add_u64 v[162:163], v[168:169], 0, s[90:91]
	s_addc_u32 s23, s23, 0
	s_add_i32 s30, s31, s84
	global_load_lds_dwordx4 v[162:163], off
	v_lshl_add_u64 v[162:163], s[22:23], 0, v[4:5]
	s_mov_b32 m0, s30
	s_nop 0
	global_load_lds_dwordx4 v[162:163], off
	v_lshl_add_u64 v[162:163], s[22:23], 0, v[142:143]
	s_add_i32 m0, s30, 0x2000
	s_nop 0
	global_load_lds_dwordx4 v[162:163], off
	v_lshl_add_u64 v[162:163], v[172:173], 0, s[90:91]
	s_mov_b32 m0, s52
	s_nop 0
	global_load_lds_dwordx4 v[162:163], off
	v_lshl_add_u64 v[162:163], v[180:181], 0, s[90:91]
	s_mov_b32 m0, s44
	s_nop 0
	global_load_lds_dwordx4 v[162:163], off
	s_waitcnt vmcnt(8)
	s_waitcnt lgkmcnt(0)
	s_barrier
	s_setprio 1
	s_waitcnt lgkmcnt(0)
	v_mfma_f32_16x16x32_bf16 v[62:65], v[130:133], v[212:215], v[62:65]
	v_mfma_f32_16x16x32_bf16 v[54:57], v[138:141], v[212:215], v[54:57]
	v_mfma_f32_16x16x32_bf16 v[46:49], v[130:133], v[220:223], v[46:49]
	v_mfma_f32_16x16x32_bf16 v[38:41], v[138:141], v[220:223], v[38:41]
	v_mfma_f32_16x16x32_bf16 v[30:33], v[130:133], v[228:231], v[30:33]
	v_mfma_f32_16x16x32_bf16 v[22:25], v[138:141], v[228:231], v[22:25]
	v_mfma_f32_16x16x32_bf16 v[14:17], v[130:133], v[236:239], v[14:17]
	v_mfma_f32_16x16x32_bf16 v[6:9], v[138:141], v[236:239], v[6:9]
	v_mfma_f32_16x16x32_bf16 v[62:65], v[134:137], v[216:219], v[62:65]
	v_mfma_f32_16x16x32_bf16 v[54:57], v[154:157], v[216:219], v[54:57]
	v_mfma_f32_16x16x32_bf16 v[46:49], v[134:137], v[224:227], v[46:49]
	v_mfma_f32_16x16x32_bf16 v[38:41], v[154:157], v[224:227], v[38:41]
	v_mfma_f32_16x16x32_bf16 v[30:33], v[134:137], v[232:235], v[30:33]
	v_mfma_f32_16x16x32_bf16 v[22:25], v[154:157], v[232:235], v[22:25]
	v_mfma_f32_16x16x32_bf16 v[14:17], v[134:137], v[240:243], v[14:17]
	v_mfma_f32_16x16x32_bf16 v[6:9], v[154:157], v[240:243], v[6:9]
	s_setprio 0
	s_setprio 1
	v_mfma_f32_16x16x32_bf16 v[58:61], v[158:161], v[212:215], v[58:61]
	v_mfma_f32_16x16x32_bf16 v[50:53], v[204:207], v[212:215], v[50:53]
	v_mfma_f32_16x16x32_bf16 v[42:45], v[158:161], v[220:223], v[42:45]
	v_mfma_f32_16x16x32_bf16 v[34:37], v[204:207], v[220:223], v[34:37]
	v_mfma_f32_16x16x32_bf16 v[26:29], v[158:161], v[228:231], v[26:29]
	v_mfma_f32_16x16x32_bf16 v[18:21], v[204:207], v[228:231], v[18:21]
	v_mfma_f32_16x16x32_bf16 v[10:13], v[158:161], v[236:239], v[10:13]
	v_mfma_f32_16x16x32_bf16 v[0:3], v[204:207], v[236:239], v[0:3]
	v_mfma_f32_16x16x32_bf16 v[58:61], v[176:179], v[216:219], v[58:61]
	v_mfma_f32_16x16x32_bf16 v[50:53], v[208:211], v[216:219], v[50:53]
	v_mfma_f32_16x16x32_bf16 v[42:45], v[176:179], v[224:227], v[42:45]
	v_mfma_f32_16x16x32_bf16 v[34:37], v[208:211], v[224:227], v[34:37]
	v_mfma_f32_16x16x32_bf16 v[26:29], v[176:179], v[232:235], v[26:29]
	v_mfma_f32_16x16x32_bf16 v[18:21], v[208:211], v[232:235], v[18:21]
	v_mfma_f32_16x16x32_bf16 v[10:13], v[176:179], v[240:243], v[10:13]
	v_mfma_f32_16x16x32_bf16 v[0:3], v[208:211], v[240:243], v[0:3]
	s_setprio 0
	s_barrier
	s_add_i32 s54, s54, 2
	s_add_u32 s46, s46, 0x100
	s_addc_u32 s47, s47, 0
	s_add_u32 s20, s20, 0x100
	s_addc_u32 s21, s21, 0
	s_cmp_gt_u32 s54, 13
	s_cbranch_scc0 .LBB0_1262
	s_and_b64 vcc, exec, s[48:49]
	s_cbranch_vccz .LBB0_1265
	s_barrier

; #define PG8_STAGE(bufoff, gbase, voff) do { _Pragma("unroll") for (int _i = 0; _i < 2; ++_i) \
;         __builtin_amdgcn_global_load_lds((const unsigned*)((const char*)(gbase) + (voff)[_i]), (LAS unsigned*)(lds + (bufoff) + ldsw + _i * 8192), 16, 0, 0); } while (0)
; #define PG8_LDA(dst, b, h) do { _Pragma("unroll") for (int m = 0; m < 4; ++m) _Pragma("unroll") for (int k = 0; k < 2; ++k) dst[m][k] = *(const LAS bf16x8*)(lds + PG8_SA(b, h) + aoff + m * 2048 + k * 1024); } while (0)
; #define PG8_LDB(dst, b, h) do { _Pragma("unroll") for (int n = 0; n < 2; ++n) _Pragma("unroll") for (int k = 0; k < 2; ++k) dst[n][k] = *(const LAS bf16x8*)(lds + PG8_SB(b, h) + boff + n * 2048 + k * 1024); } while (0)
; #define PG8_MMA(ai, bj, At, Bt) do { __builtin_amdgcn_s_setprio(1); _Pragma("unroll") for (int m = 0; m < 4; ++m) _Pragma("unroll") for (int n = 0; n < 2; ++n) _Pragma("unroll") for (int k = 0; k < 2; ++k) \
;         acc[ai][bj][m][n] = __builtin_amdgcn_mfma_f32_16x16x32_bf16(Bt[n][k], At[m][k], acc[ai][bj][m][n], 0, 0, 0); __builtin_amdgcn_s_setprio(0); } while (0)
; #define PG8_WAIT_V(n) asm volatile("s_waitcnt vmcnt(" #n ")" ::: "memory")
; #define PG8_WAIT_L(n) asm volatile("s_waitcnt lgkmcnt(" #n ")" ::: "memory")
; #define PG8_BAR __builtin_amdgcn_s_barrier()
; #define PG8_SCHED __builtin_amdgcn_sched_barrier(0)
; template <class Epi, bool ALIGN_EPI>
; __device__ __forceinline__ void gemm_phase(LAS unsigned char* lds, const Gemm g, const StaticOrder& S, const Epi& E) {
;     ...
;         const bool has_next = S.next(ui + 1, nxt);
;         const char* nA = has_next ? (const char*)g.A + (size_t)nxt.pm * tstepA : cA; const char* nB = has_next ? (const char*)g.Bt + (size_t)nxt.pn * tstepB : cB;
;         for (int t = 0; t < nt; t += 2) {
;             const bool last = (t == nt - 2);
;             const char* a1 = cA + (size_t)(t + 1) * kstep;
;             const char* a2 = last ? nA : cA + (size_t)(t + 2) * kstep; const char* b2 = last ? nB : cB + (size_t)(t + 2) * kstep;
;             const char* a3 = a2 + kstep; const char* b3 = b2 + kstep;
;             PG8_LDB(B0, 0, 0); PG8_LDB(B1, 0, 1); PG8_SCHED; PG8_LDA(At, 0, 0); PG8_STAGE(PG8_SA(1, 1), a1 + hstepA, voffA);
;             PG8_WAIT_V(8); PG8_WAIT_L(0); PG8_BAR; PG8_MMA(0, 0, At, B0); PG8_MMA(0, 1, At, B1); PG8_BAR; PG8_SCHED;
.LBB0_1482:
	s_ashr_i32 s45, s44, 31
	s_lshl_b64 s[24:25], s[44:45], 19
	s_add_u32 s48, s8, s24
	s_addc_u32 s49, s9, s25
	s_and_b64 s[24:25], s[40:41], exec
	s_cselect_b32 s7, s49, s51
	s_cselect_b32 s21, s48, s50
	s_ashr_i32 s19, s18, 31
	s_lshl_b64 s[24:25], s[18:19], 19
	s_add_u32 s56, s5, s24
	s_addc_u32 s57, s53, s25
	s_and_b64 s[24:25], s[40:41], exec
	s_cselect_b32 s19, s57, s43
	s_cselect_b32 s23, s56, s42
	s_add_u32 s24, s42, 0x100
	s_addc_u32 s25, s43, 0
	s_add_u32 s42, s50, 0x40080
	s_addc_u32 s43, s51, 0
	s_mov_b32 s28, -2
.LBB0_1483:
	s_add_u32 s29, s42, 0xfffc0080
	s_addc_u32 s45, s43, -1
	s_add_i32 s47, 0, 0x10000
	s_cmp_eq_u32 s28, 12
	s_cselect_b32 s61, s7, s45
	s_cselect_b32 s60, s21, s29
	s_cselect_b32 s51, s19, s25
	s_cselect_b32 s50, s23, s24
	s_add_i32 s29, 0, 0x14000
	v_add_u32_e32 v154, s47, v165
	v_add_u32_e32 v162, s29, v165
	ds_read_b128 v[142:145], v154
	ds_read_b128 v[146:149], v154 offset:1024
	ds_read_b128 v[150:153], v154 offset:2048
	ds_read_b128 v[154:157], v154 offset:3072
	ds_read_b128 v[158:161], v162
	ds_read_b128 v[168:171], v162 offset:1024
	ds_read_b128 v[172:175], v162 offset:2048
	ds_read_b128 v[176:179], v162 offset:3072
	v_lshl_add_u64 v[162:163], s[42:43], 0, v[140:141]
	s_add_i32 m0, s84, 0xc000
	ds_read_b128 v[204:207], v167
	ds_read_b128 v[208:211], v167 offset:1024
	ds_read_b128 v[212:215], v167 offset:2048
	ds_read_b128 v[216:219], v167 offset:3072
	ds_read_b128 v[220:223], v167 offset:4096
	ds_read_b128 v[224:227], v167 offset:5120
	ds_read_b128 v[228:231], v167 offset:6144
	ds_read_b128 v[232:235], v167 offset:7168
	global_load_lds_dwordx4 v[162:163], off
	v_lshl_add_u64 v[162:163], s[42:43], 0, v[138:139]
	s_add_i32 m0, s84, 0xe000
	s_nop 0
	global_load_lds_dwordx4 v[162:163], off
	s_cmp_lg_u32 s28, -2
	s_cbranch_scc1 .Lmy_nz_a
	v_mov_b64_e32 v[0:1], 0
	v_mov_b64_e32 v[2:3], 0
	v_mov_b64_e32 v[6:7], 0
	v_mov_b64_e32 v[8:9], 0
	v_mov_b64_e32 v[10:11], 0
	v_mov_b64_e32 v[12:13], 0
	v_mov_b64_e32 v[14:15], 0
	v_mov_b64_e32 v[16:17], 0
	v_mov_b64_e32 v[18:19], 0
	v_mov_b64_e32 v[20:21], 0
	v_mov_b64_e32 v[22:23], 0
	v_mov_b64_e32 v[24:25], 0
	v_mov_b64_e32 v[26:27], 0
	v_mov_b64_e32 v[28:29], 0
	v_mov_b64_e32 v[30:31], 0
	v_mov_b64_e32 v[32:33], 0
	v_mov_b64_e32 v[34:35], 0
	v_mov_b64_e32 v[36:37], 0
	v_mov_b64_e32 v[38:39], 0
	v_mov_b64_e32 v[40:41], 0
	v_mov_b64_e32 v[42:43], 0
	v_mov_b64_e32 v[44:45], 0
	v_mov_b64_e32 v[46:47], 0
	v_mov_b64_e32 v[48:49], 0
	v_mov_b64_e32 v[50:51], 0
	v_mov_b64_e32 v[52:53], 0
	v_mov_b64_e32 v[54:55], 0
	v_mov_b64_e32 v[56:57], 0
	v_mov_b64_e32 v[58:59], 0
	v_mov_b64_e32 v[60:61], 0
	v_mov_b64_e32 v[62:63], 0
	v_mov_b64_e32 v[64:65], 0
	v_mov_b64_e32 v[66:67], 0
	v_mov_b64_e32 v[68:69], 0
	v_mov_b64_e32 v[70:71], 0
	v_mov_b64_e32 v[72:73], 0
	v_mov_b64_e32 v[74:75], 0
	v_mov_b64_e32 v[76:77], 0
	v_mov_b64_e32 v[78:79], 0
	v_mov_b64_e32 v[80:81], 0
	v_mov_b64_e32 v[82:83], 0
	v_mov_b64_e32 v[84:85], 0
	v_mov_b64_e32 v[86:87], 0
	v_mov_b64_e32 v[88:89], 0
	v_mov_b64_e32 v[90:91], 0
	v_mov_b64_e32 v[92:93], 0
	v_mov_b64_e32 v[94:95], 0
	v_mov_b64_e32 v[96:97], 0
	v_mov_b64_e32 v[98:99], 0
	v_mov_b64_e32 v[100:101], 0
	v_mov_b64_e32 v[102:103], 0
	v_mov_b64_e32 v[104:105], 0
	v_mov_b64_e32 v[106:107], 0
	v_mov_b64_e32 v[108:109], 0
	v_mov_b64_e32 v[110:111], 0
	v_mov_b64_e32 v[112:113], 0
	v_mov_b64_e32 v[114:115], 0
	v_mov_b64_e32 v[116:117], 0
	v_mov_b64_e32 v[118:119], 0
	v_mov_b64_e32 v[120:121], 0
	v_mov_b64_e32 v[122:123], 0
	v_mov_b64_e32 v[124:125], 0
	v_mov_b64_e32 v[126:127], 0
	v_mov_b64_e32 v[128:129], 0
.Lmy_nz_a:
	s_waitcnt vmcnt(8)
	s_waitcnt lgkmcnt(0)
	s_barrier
	s_setprio 1
	s_waitcnt lgkmcnt(0)
	v_mfma_f32_16x16x32_bf16 v[126:129], v[142:145], v[204:207], v[126:129]
	v_mfma_f32_16x16x32_bf16 v[122:125], v[150:153], v[204:207], v[122:125]
	v_mfma_f32_16x16x32_bf16 v[110:113], v[142:145], v[212:215], v[110:113]
	v_mfma_f32_16x16x32_bf16 v[106:109], v[150:153], v[212:215], v[106:109]
	v_mfma_f32_16x16x32_bf16 v[94:97], v[142:145], v[220:223], v[94:97]
	v_mfma_f32_16x16x32_bf16 v[90:93], v[150:153], v[220:223], v[90:93]
	v_mfma_f32_16x16x32_bf16 v[78:81], v[142:145], v[228:231], v[78:81]
	v_mfma_f32_16x16x32_bf16 v[74:77], v[150:153], v[228:231], v[74:77]
	v_mfma_f32_16x16x32_bf16 v[126:129], v[146:149], v[208:211], v[126:129]
	v_mfma_f32_16x16x32_bf16 v[122:125], v[154:157], v[208:211], v[122:125]
	v_mfma_f32_16x16x32_bf16 v[110:113], v[146:149], v[216:219], v[110:113]
	v_mfma_f32_16x16x32_bf16 v[106:109], v[154:157], v[216:219], v[106:109]
	v_mfma_f32_16x16x32_bf16 v[94:97], v[146:149], v[224:227], v[94:97]
	v_mfma_f32_16x16x32_bf16 v[90:93], v[154:157], v[224:227], v[90:93]
	v_mfma_f32_16x16x32_bf16 v[78:81], v[146:149], v[232:235], v[78:81]
	v_mfma_f32_16x16x32_bf16 v[74:77], v[154:157], v[232:235], v[74:77]
	s_setprio 0
	s_setprio 1
	v_mfma_f32_16x16x32_bf16 v[118:121], v[158:161], v[204:207], v[118:121]
	v_mfma_f32_16x16x32_bf16 v[114:117], v[172:175], v[204:207], v[114:117]
	v_mfma_f32_16x16x32_bf16 v[102:105], v[158:161], v[212:215], v[102:105]
	v_mfma_f32_16x16x32_bf16 v[98:101], v[172:175], v[212:215], v[98:101]
	v_mfma_f32_16x16x32_bf16 v[86:89], v[158:161], v[220:223], v[86:89]
	v_mfma_f32_16x16x32_bf16 v[82:85], v[172:175], v[220:223], v[82:85]
	v_mfma_f32_16x16x32_bf16 v[70:73], v[158:161], v[228:231], v[70:73]
	v_mfma_f32_16x16x32_bf16 v[66:69], v[172:175], v[228:231], v[66:69]
	v_mfma_f32_16x16x32_bf16 v[118:121], v[168:171], v[208:211], v[118:121]
	v_mfma_f32_16x16x32_bf16 v[114:117], v[176:179], v[208:211], v[114:117]
	v_mfma_f32_16x16x32_bf16 v[102:105], v[168:171], v[216:219], v[102:105]
	v_mfma_f32_16x16x32_bf16 v[98:101], v[176:179], v[216:219], v[98:101]
	v_mfma_f32_16x16x32_bf16 v[86:89], v[168:171], v[224:227], v[86:89]
	v_mfma_f32_16x16x32_bf16 v[82:85], v[176:179], v[224:227], v[82:85]
	v_mfma_f32_16x16x32_bf16 v[70:73], v[168:171], v[232:235], v[70:73]
	v_mfma_f32_16x16x32_bf16 v[66:69], v[176:179], v[232:235], v[66:69]
	s_setprio 0
	s_barrier
; #define PG8_STAGE(bufoff, gbase, voff) do { _Pragma("unroll") for (int _i = 0; _i < 2; ++_i) \
;         __builtin_amdgcn_global_load_lds((const unsigned*)((const char*)(gbase) + (voff)[_i]), (LAS unsigned*)(lds + (bufoff) + ldsw + _i * 8192), 16, 0, 0); } while (0)
; #define PG8_LDA(dst, b, h) do { _Pragma("unroll") for (int m = 0; m < 4; ++m) _Pragma("unroll") for (int k = 0; k < 2; ++k) dst[m][k] = *(const LAS bf16x8*)(lds + PG8_SA(b, h) + aoff + m * 2048 + k * 1024); } while (0)
; #define PG8_LDB(dst, b, h) do { _Pragma("unroll") for (int n = 0; n < 2; ++n) _Pragma("unroll") for (int k = 0; k < 2; ++k) dst[n][k] = *(const LAS bf16x8*)(lds + PG8_SB(b, h) + boff + n * 2048 + k * 1024); } while (0)
; #define PG8_MMA(ai, bj, At, Bt) do { __builtin_amdgcn_s_setprio(1); _Pragma("unroll") for (int m = 0; m < 4; ++m) _Pragma("unroll") for (int n = 0; n < 2; ++n) _Pragma("unroll") for (int k = 0; k < 2; ++k) \
;         acc[ai][bj][m][n] = __builtin_amdgcn_mfma_f32_16x16x32_bf16(Bt[n][k], At[m][k], acc[ai][bj][m][n], 0, 0, 0); __builtin_amdgcn_s_setprio(0); } while (0)
; #define PG8_WAIT_V(n) asm volatile("s_waitcnt vmcnt(" #n ")" ::: "memory")
; #define PG8_WAIT_L(n) asm volatile("s_waitcnt lgkmcnt(" #n ")" ::: "memory")
; #define PG8_BAR __builtin_amdgcn_s_barrier()
; #define PG8_SCHED __builtin_amdgcn_sched_barrier(0)
; template <class Epi, bool ALIGN_EPI>
; __device__ __forceinline__ void gemm_phase(LAS unsigned char* lds, const Gemm g, const StaticOrder& S, const Epi& E) {
;     ...
;             PG8_LDA(At, 0, 1); PG8_STAGE(PG8_SB(0, 0), b2, voffB); PG8_STAGE(PG8_SB(0, 1), b2 + hstepB, voffB); PG8_STAGE(PG8_SA(0, 0), a2, voffA);
;             PG8_WAIT_V(8); PG8_WAIT_L(0); PG8_BAR; PG8_MMA(1, 0, At, B0); PG8_MMA(1, 1, At, B1); PG8_BAR; PG8_SCHED;
;             PG8_LDB(B0, 1, 0); PG8_LDB(B1, 1, 1); PG8_SCHED; PG8_LDA(At, 1, 0); PG8_STAGE(PG8_SA(0, 1), a2 + hstepA, voffA);
;             PG8_WAIT_V(8); PG8_WAIT_L(0); PG8_BAR; PG8_MMA(0, 0, At, B0); PG8_MMA(0, 1, At, B1); PG8_BAR; PG8_SCHED;
	s_add_i32 s45, s47, s52
	v_lshl_add_u64 v[162:163], s[50:51], 0, v[4:5]
	s_mov_b32 m0, s45
	ds_read_b128 v[204:207], v167 offset:16384
	ds_read_b128 v[208:211], v167 offset:17408
	ds_read_b128 v[212:215], v167 offset:18432
	ds_read_b128 v[216:219], v167 offset:19456
	ds_read_b128 v[220:223], v167 offset:20480
	ds_read_b128 v[224:227], v167 offset:21504
	ds_read_b128 v[228:231], v167 offset:22528
	ds_read_b128 v[232:235], v167 offset:23552
	global_load_lds_dwordx4 v[162:163], off
	s_add_i32 m0, s45, 0x2000
	s_add_u32 s58, s50, 0x40000
	v_lshl_add_u64 v[180:181], s[50:51], 0, v[134:135]
	s_addc_u32 s59, s51, 0
	s_add_i32 s29, s29, s52
	global_load_lds_dwordx4 v[180:181], off
	v_lshl_add_u64 v[236:237], s[58:59], 0, v[4:5]
	s_mov_b32 m0, s29
	v_lshl_add_u64 v[238:239], s[60:61], 0, v[132:133]
	global_load_lds_dwordx4 v[236:237], off
	v_lshl_add_u64 v[236:237], s[58:59], 0, v[134:135]
	s_add_i32 m0, s29, 0x2000
	s_nop 0
	global_load_lds_dwordx4 v[236:237], off
	v_lshl_add_u64 v[236:237], s[60:61], 0, v[130:131]
	s_mov_b32 m0, s84
	s_nop 0
	global_load_lds_dwordx4 v[236:237], off
	s_mov_b32 m0, s70
	s_nop 0
	global_load_lds_dwordx4 v[238:239], off
	s_waitcnt vmcnt(8)
	s_waitcnt lgkmcnt(0)
	s_barrier
	s_setprio 1
	s_waitcnt lgkmcnt(0)
	v_mfma_f32_16x16x32_bf16 v[62:65], v[142:145], v[204:207], v[62:65]
	v_mfma_f32_16x16x32_bf16 v[58:61], v[150:153], v[204:207], v[58:61]
	v_mfma_f32_16x16x32_bf16 v[46:49], v[142:145], v[212:215], v[46:49]
	v_mfma_f32_16x16x32_bf16 v[42:45], v[150:153], v[212:215], v[42:45]
	v_mfma_f32_16x16x32_bf16 v[30:33], v[142:145], v[220:223], v[30:33]
	v_mfma_f32_16x16x32_bf16 v[26:29], v[150:153], v[220:223], v[26:29]
	v_mfma_f32_16x16x32_bf16 v[14:17], v[142:145], v[228:231], v[14:17]
	v_mfma_f32_16x16x32_bf16 v[10:13], v[150:153], v[228:231], v[10:13]
	v_mfma_f32_16x16x32_bf16 v[62:65], v[146:149], v[208:211], v[62:65]
	v_mfma_f32_16x16x32_bf16 v[58:61], v[154:157], v[208:211], v[58:61]
	v_mfma_f32_16x16x32_bf16 v[46:49], v[146:149], v[216:219], v[46:49]
	v_mfma_f32_16x16x32_bf16 v[42:45], v[154:157], v[216:219], v[42:45]
	v_mfma_f32_16x16x32_bf16 v[30:33], v[146:149], v[224:227], v[30:33]
	v_mfma_f32_16x16x32_bf16 v[26:29], v[154:157], v[224:227], v[26:29]
	v_mfma_f32_16x16x32_bf16 v[14:17], v[146:149], v[232:235], v[14:17]
	v_mfma_f32_16x16x32_bf16 v[10:13], v[154:157], v[232:235], v[10:13]
	s_setprio 0
	s_setprio 1
	v_mfma_f32_16x16x32_bf16 v[54:57], v[158:161], v[204:207], v[54:57]
	v_mfma_f32_16x16x32_bf16 v[50:53], v[172:175], v[204:207], v[50:53]
	v_mfma_f32_16x16x32_bf16 v[38:41], v[158:161], v[212:215], v[38:41]
	v_mfma_f32_16x16x32_bf16 v[34:37], v[172:175], v[212:215], v[34:37]
	v_mfma_f32_16x16x32_bf16 v[22:25], v[158:161], v[220:223], v[22:25]
	v_mfma_f32_16x16x32_bf16 v[18:21], v[172:175], v[220:223], v[18:21]
	v_mfma_f32_16x16x32_bf16 v[6:9], v[158:161], v[228:231], v[6:9]
	v_mfma_f32_16x16x32_bf16 v[0:3], v[172:175], v[228:231], v[0:3]
	v_mfma_f32_16x16x32_bf16 v[54:57], v[168:171], v[208:211], v[54:57]
	v_mfma_f32_16x16x32_bf16 v[50:53], v[176:179], v[208:211], v[50:53]
	v_mfma_f32_16x16x32_bf16 v[38:41], v[168:171], v[216:219], v[38:41]
	v_mfma_f32_16x16x32_bf16 v[34:37], v[176:179], v[216:219], v[34:37]
	v_mfma_f32_16x16x32_bf16 v[22:25], v[168:171], v[224:227], v[22:25]
	v_mfma_f32_16x16x32_bf16 v[18:21], v[176:179], v[224:227], v[18:21]
	v_mfma_f32_16x16x32_bf16 v[6:9], v[168:171], v[232:235], v[6:9]
	v_mfma_f32_16x16x32_bf16 v[0:3], v[176:179], v[232:235], v[0:3]
	s_setprio 0
	s_barrier
	s_add_i32 s29, 0, 0x18000
	s_add_i32 s45, 0, 0x1c000
	v_add_u32_e32 v154, s29, v165
	v_add_u32_e32 v176, s45, v165
	ds_read_b128 v[142:145], v154
	ds_read_b128 v[146:149], v154 offset:1024
	ds_read_b128 v[150:153], v154 offset:2048
	ds_read_b128 v[154:157], v154 offset:3072
	ds_read_b128 v[158:161], v176
	ds_read_b128 v[168:171], v176 offset:1024
	ds_read_b128 v[172:175], v176 offset:2048
	ds_read_b128 v[176:179], v176 offset:3072
	s_add_u32 s58, s60, 0x40000
	s_addc_u32 s59, s61, 0
	s_mov_b32 m0, s64
	v_lshl_add_u64 v[240:241], s[58:59], 0, v[130:131]
	ds_read_b128 v[204:207], v167 offset:32768
	ds_read_b128 v[208:211], v167 offset:33792
	ds_read_b128 v[212:215], v167 offset:34816
	ds_read_b128 v[216:219], v167 offset:35840
	ds_read_b128 v[220:223], v167 offset:36864
	ds_read_b128 v[224:227], v167 offset:37888
	ds_read_b128 v[228:231], v167 offset:38912
	ds_read_b128 v[232:235], v167 offset:39936
	global_load_lds_dwordx4 v[240:241], off
	v_lshl_add_u64 v[240:241], s[58:59], 0, v[132:133]
	s_mov_b32 m0, s71
	s_nop 0
	global_load_lds_dwordx4 v[240:241], off
	s_waitcnt vmcnt(8)
	s_waitcnt lgkmcnt(0)
	s_barrier
; #define PG8_STAGE(bufoff, gbase, voff) do { _Pragma("unroll") for (int _i = 0; _i < 2; ++_i) \
;         __builtin_amdgcn_global_load_lds((const unsigned*)((const char*)(gbase) + (voff)[_i]), (LAS unsigned*)(lds + (bufoff) + ldsw + _i * 8192), 16, 0, 0); } while (0)
; #define PG8_LDA(dst, b, h) do { _Pragma("unroll") for (int m = 0; m < 4; ++m) _Pragma("unroll") for (int k = 0; k < 2; ++k) dst[m][k] = *(const LAS bf16x8*)(lds + PG8_SA(b, h) + aoff + m * 2048 + k * 1024); } while (0)
; #define PG8_MMA(ai, bj, At, Bt) do { __builtin_amdgcn_s_setprio(1); _Pragma("unroll") for (int m = 0; m < 4; ++m) _Pragma("unroll") for (int n = 0; n < 2; ++n) _Pragma("unroll") for (int k = 0; k < 2; ++k) \
;         acc[ai][bj][m][n] = __builtin_amdgcn_mfma_f32_16x16x32_bf16(Bt[n][k], At[m][k], acc[ai][bj][m][n], 0, 0, 0); __builtin_amdgcn_s_setprio(0); } while (0)
; #define PG8_WAIT_V(n) asm volatile("s_waitcnt vmcnt(" #n ")" ::: "memory")
; #define PG8_WAIT_L(n) asm volatile("s_waitcnt lgkmcnt(" #n ")" ::: "memory")
; #define PG8_BAR __builtin_amdgcn_s_barrier()
; #define PG8_SCHED __builtin_amdgcn_sched_barrier(0)
; template <class Epi, bool ALIGN_EPI>
; __device__ __forceinline__ void gemm_phase(LAS unsigned char* lds, const Gemm g, const StaticOrder& S, const Epi& E) {
;     ...
;             PG8_WAIT_V(8); PG8_WAIT_L(0); PG8_BAR; PG8_MMA(0, 0, At, B0); PG8_MMA(0, 1, At, B1); PG8_BAR; PG8_SCHED;
;             PG8_LDA(At, 1, 1); PG8_STAGE(PG8_SB(1, 0), b3, voffB); PG8_STAGE(PG8_SB(1, 1), b3 + hstepB, voffB); PG8_STAGE(PG8_SA(1, 0), a3, voffA);
;             PG8_WAIT_V(8); PG8_WAIT_L(0); PG8_BAR; PG8_MMA(1, 0, At, B0); PG8_MMA(1, 1, At, B1); PG8_BAR; PG8_SCHED;
;         }
;         if constexpr (ALIGN_EPI) { if (wr == 0) PG8_BAR; }
	s_setprio 1
	s_waitcnt lgkmcnt(0)
	v_mfma_f32_16x16x32_bf16 v[126:129], v[142:145], v[204:207], v[126:129]
	v_mfma_f32_16x16x32_bf16 v[122:125], v[150:153], v[204:207], v[122:125]
	v_mfma_f32_16x16x32_bf16 v[110:113], v[142:145], v[212:215], v[110:113]
	v_mfma_f32_16x16x32_bf16 v[106:109], v[150:153], v[212:215], v[106:109]
	v_mfma_f32_16x16x32_bf16 v[94:97], v[142:145], v[220:223], v[94:97]
	v_mfma_f32_16x16x32_bf16 v[90:93], v[150:153], v[220:223], v[90:93]
	v_mfma_f32_16x16x32_bf16 v[78:81], v[142:145], v[228:231], v[78:81]
	v_mfma_f32_16x16x32_bf16 v[74:77], v[150:153], v[228:231], v[74:77]
	v_mfma_f32_16x16x32_bf16 v[126:129], v[146:149], v[208:211], v[126:129]
	v_mfma_f32_16x16x32_bf16 v[122:125], v[154:157], v[208:211], v[122:125]
	v_mfma_f32_16x16x32_bf16 v[110:113], v[146:149], v[216:219], v[110:113]
	v_mfma_f32_16x16x32_bf16 v[106:109], v[154:157], v[216:219], v[106:109]
	v_mfma_f32_16x16x32_bf16 v[94:97], v[146:149], v[224:227], v[94:97]
	v_mfma_f32_16x16x32_bf16 v[90:93], v[154:157], v[224:227], v[90:93]
	v_mfma_f32_16x16x32_bf16 v[78:81], v[146:149], v[232:235], v[78:81]
	v_mfma_f32_16x16x32_bf16 v[74:77], v[154:157], v[232:235], v[74:77]
	s_setprio 0
	s_setprio 1
	v_mfma_f32_16x16x32_bf16 v[118:121], v[158:161], v[204:207], v[118:121]
	v_mfma_f32_16x16x32_bf16 v[114:117], v[172:175], v[204:207], v[114:117]
	v_mfma_f32_16x16x32_bf16 v[102:105], v[158:161], v[212:215], v[102:105]
	v_mfma_f32_16x16x32_bf16 v[98:101], v[172:175], v[212:215], v[98:101]
	v_mfma_f32_16x16x32_bf16 v[86:89], v[158:161], v[220:223], v[86:89]
	v_mfma_f32_16x16x32_bf16 v[82:85], v[172:175], v[220:223], v[82:85]
	v_mfma_f32_16x16x32_bf16 v[70:73], v[158:161], v[228:231], v[70:73]
	v_mfma_f32_16x16x32_bf16 v[66:69], v[172:175], v[228:231], v[66:69]
	v_mfma_f32_16x16x32_bf16 v[118:121], v[168:171], v[208:211], v[118:121]
	v_mfma_f32_16x16x32_bf16 v[114:117], v[176:179], v[208:211], v[114:117]
	v_mfma_f32_16x16x32_bf16 v[102:105], v[168:171], v[216:219], v[102:105]
	v_mfma_f32_16x16x32_bf16 v[98:101], v[176:179], v[216:219], v[98:101]
	v_mfma_f32_16x16x32_bf16 v[86:89], v[168:171], v[224:227], v[86:89]
	v_mfma_f32_16x16x32_bf16 v[82:85], v[176:179], v[224:227], v[82:85]
	v_mfma_f32_16x16x32_bf16 v[70:73], v[168:171], v[232:235], v[70:73]
	v_mfma_f32_16x16x32_bf16 v[66:69], v[176:179], v[232:235], v[66:69]
	s_setprio 0
	s_barrier
	s_add_i32 s29, s29, s52
	v_lshl_add_u64 v[162:163], v[162:163], 0, s[90:91]
	s_mov_b32 m0, s29
	ds_read_b128 v[204:207], v167 offset:49152
	ds_read_b128 v[208:211], v167 offset:50176
	ds_read_b128 v[212:215], v167 offset:51200
	ds_read_b128 v[216:219], v167 offset:52224
	ds_read_b128 v[220:223], v167 offset:53248
	ds_read_b128 v[224:227], v167 offset:54272
	ds_read_b128 v[228:231], v167 offset:55296
	ds_read_b128 v[232:235], v167 offset:56320
	global_load_lds_dwordx4 v[162:163], off
	s_add_i32 m0, s29, 0x2000
	s_add_u32 s50, s50, 0x40080
	v_lshl_add_u64 v[162:163], v[180:181], 0, s[90:91]
	s_addc_u32 s51, s51, 0
	s_add_i32 s29, s45, s52
	global_load_lds_dwordx4 v[162:163], off
	v_lshl_add_u64 v[162:163], s[50:51], 0, v[4:5]
	s_mov_b32 m0, s29
	s_nop 0
	global_load_lds_dwordx4 v[162:163], off
	v_lshl_add_u64 v[162:163], s[50:51], 0, v[134:135]
	s_add_i32 m0, s29, 0x2000
	s_nop 0
	global_load_lds_dwordx4 v[162:163], off
	v_lshl_add_u64 v[162:163], v[236:237], 0, s[90:91]
	s_mov_b32 m0, s4
	s_nop 0
	global_load_lds_dwordx4 v[162:163], off
	v_lshl_add_u64 v[162:163], v[238:239], 0, s[90:91]
	s_mov_b32 m0, s92
	s_nop 0
	global_load_lds_dwordx4 v[162:163], off
	s_waitcnt vmcnt(8)
	s_waitcnt lgkmcnt(0)
	s_barrier
	s_setprio 1
	s_waitcnt lgkmcnt(0)
	v_mfma_f32_16x16x32_bf16 v[62:65], v[142:145], v[204:207], v[62:65]
	v_mfma_f32_16x16x32_bf16 v[58:61], v[150:153], v[204:207], v[58:61]
	v_mfma_f32_16x16x32_bf16 v[46:49], v[142:145], v[212:215], v[46:49]
	v_mfma_f32_16x16x32_bf16 v[42:45], v[150:153], v[212:215], v[42:45]
	v_mfma_f32_16x16x32_bf16 v[30:33], v[142:145], v[220:223], v[30:33]
	v_mfma_f32_16x16x32_bf16 v[26:29], v[150:153], v[220:223], v[26:29]
	v_mfma_f32_16x16x32_bf16 v[14:17], v[142:145], v[228:231], v[14:17]
	v_mfma_f32_16x16x32_bf16 v[10:13], v[150:153], v[228:231], v[10:13]
	v_mfma_f32_16x16x32_bf16 v[62:65], v[146:149], v[208:211], v[62:65]
	v_mfma_f32_16x16x32_bf16 v[58:61], v[154:157], v[208:211], v[58:61]
	v_mfma_f32_16x16x32_bf16 v[46:49], v[146:149], v[216:219], v[46:49]
	v_mfma_f32_16x16x32_bf16 v[42:45], v[154:157], v[216:219], v[42:45]
	v_mfma_f32_16x16x32_bf16 v[30:33], v[146:149], v[224:227], v[30:33]
	v_mfma_f32_16x16x32_bf16 v[26:29], v[154:157], v[224:227], v[26:29]
	v_mfma_f32_16x16x32_bf16 v[14:17], v[146:149], v[232:235], v[14:17]
	v_mfma_f32_16x16x32_bf16 v[10:13], v[154:157], v[232:235], v[10:13]
	s_setprio 0
	s_setprio 1
	v_mfma_f32_16x16x32_bf16 v[54:57], v[158:161], v[204:207], v[54:57]
	v_mfma_f32_16x16x32_bf16 v[50:53], v[172:175], v[204:207], v[50:53]
	v_mfma_f32_16x16x32_bf16 v[38:41], v[158:161], v[212:215], v[38:41]
	v_mfma_f32_16x16x32_bf16 v[34:37], v[172:175], v[212:215], v[34:37]
	v_mfma_f32_16x16x32_bf16 v[22:25], v[158:161], v[220:223], v[22:25]
	v_mfma_f32_16x16x32_bf16 v[18:21], v[172:175], v[220:223], v[18:21]
	v_mfma_f32_16x16x32_bf16 v[6:9], v[158:161], v[228:231], v[6:9]
	v_mfma_f32_16x16x32_bf16 v[0:3], v[172:175], v[228:231], v[0:3]
	v_mfma_f32_16x16x32_bf16 v[54:57], v[168:171], v[208:211], v[54:57]
	v_mfma_f32_16x16x32_bf16 v[50:53], v[176:179], v[208:211], v[50:53]
	v_mfma_f32_16x16x32_bf16 v[38:41], v[168:171], v[216:219], v[38:41]
	v_mfma_f32_16x16x32_bf16 v[34:37], v[176:179], v[216:219], v[34:37]
	v_mfma_f32_16x16x32_bf16 v[22:25], v[168:171], v[224:227], v[22:25]
	v_mfma_f32_16x16x32_bf16 v[18:21], v[176:179], v[224:227], v[18:21]
	v_mfma_f32_16x16x32_bf16 v[6:9], v[168:171], v[232:235], v[6:9]
	v_mfma_f32_16x16x32_bf16 v[0:3], v[176:179], v[232:235], v[0:3]
	s_setprio 0
	s_barrier
	s_add_i32 s28, s28, 2
	s_add_u32 s24, s24, 0x100
	s_addc_u32 s25, s25, 0
	s_add_u32 s42, s42, 0x100
	s_addc_u32 s43, s43, 0
	s_cmp_gt_u32 s28, 13
	s_cbranch_scc0 .LBB0_1483
	s_and_b64 vcc, exec, s[16:17]
	s_cbranch_vccz .LBB0_1486
	s_barrier
